# baseline (speedup 1.0000x reference)
.LBB0_389:
	ds_read_b128 v[4:7], v233 offset:32768
	ds_read_b128 v[8:11], v233 offset:40960
	ds_read_b128 v[12:15], v234 offset:32768
	v_add_u32_e32 v3, v225, v227
	s_cmp_le_i32 s81, s80
	s_waitcnt vmcnt(11) lgkmcnt(2)
	v_mfma_f32_32x32x16_bf16 v[98:113], v[4:7], v[126:129], 0
	ds_read_b128 v[4:7], v234 offset:40960
	s_waitcnt lgkmcnt(2)
	v_mfma_f32_32x32x16_bf16 v[82:97], v[8:11], v[126:129], 0
	ds_read_b128 v[8:11], v235 offset:32768
	s_waitcnt vmcnt(10) lgkmcnt(2)
	v_mfma_f32_32x32x16_bf16 v[98:113], v[12:15], v[130:133], v[98:113]
	ds_read_b128 v[12:15], v235 offset:40960
	s_waitcnt lgkmcnt(2)
	v_mfma_f32_32x32x16_bf16 v[82:97], v[4:7], v[130:133], v[82:97]
	ds_read_b128 v[4:7], v236 offset:32768
	s_waitcnt vmcnt(9) lgkmcnt(2)
	v_mfma_f32_32x32x16_bf16 v[98:113], v[8:11], v[138:141], v[98:113]
	ds_read_b128 v[8:11], v236 offset:40960
	s_waitcnt lgkmcnt(2)
	v_mfma_f32_32x32x16_bf16 v[82:97], v[12:15], v[138:141], v[82:97]
	ds_read_b128 v[12:15], v237 offset:32768
	s_waitcnt vmcnt(8) lgkmcnt(2)
	v_mfma_f32_32x32x16_bf16 v[98:113], v[4:7], v[142:145], v[98:113]
	ds_read_b128 v[4:7], v237 offset:40960
	s_waitcnt lgkmcnt(2)
	v_mfma_f32_32x32x16_bf16 v[82:97], v[8:11], v[142:145], v[82:97]
	ds_read_b128 v[8:11], v238 offset:32768
	s_waitcnt vmcnt(7) lgkmcnt(2)
	v_mfma_f32_32x32x16_bf16 v[98:113], v[12:15], v[146:149], v[98:113]
	ds_read_b128 v[12:15], v238 offset:40960
	s_waitcnt lgkmcnt(2)
	v_mfma_f32_32x32x16_bf16 v[82:97], v[4:7], v[146:149], v[82:97]
	ds_read_b128 v[4:7], v239 offset:32768
	s_waitcnt vmcnt(6) lgkmcnt(2)
	v_mfma_f32_32x32x16_bf16 v[98:113], v[8:11], v[150:153], v[98:113]
	ds_read_b128 v[8:11], v239 offset:40960
	s_waitcnt lgkmcnt(2)
	v_mfma_f32_32x32x16_bf16 v[82:97], v[12:15], v[150:153], v[82:97]
	ds_read_b128 v[12:15], v240 offset:32768
	s_waitcnt vmcnt(5) lgkmcnt(2)
	v_mfma_f32_32x32x16_bf16 v[98:113], v[4:7], v[154:157], v[98:113]
	ds_read_b128 v[4:7], v240 offset:40960
	s_waitcnt lgkmcnt(2)
	v_mfma_f32_32x32x16_bf16 v[82:97], v[8:11], v[154:157], v[82:97]
	ds_read_b128 v[8:11], v3
	s_waitcnt vmcnt(4) lgkmcnt(2)
	v_mfma_f32_32x32x16_bf16 v[98:113], v[12:15], v[158:161], v[98:113]
	ds_read_b128 v[12:15], v3 offset:4096
	v_add_u32_e32 v3, v225, v228
	s_waitcnt lgkmcnt(2)
	v_mfma_f32_32x32x16_bf16 v[82:97], v[4:7], v[158:161], v[82:97]
	ds_read_b128 v[4:7], v3
	s_waitcnt vmcnt(3) lgkmcnt(2)
	v_mfma_f32_32x32x16_bf16 v[98:113], v[8:11], v[162:165], v[98:113]
	ds_read_b128 v[8:11], v3 offset:4096
	v_add_u32_e32 v3, v225, v229
	s_waitcnt lgkmcnt(2)
	v_mfma_f32_32x32x16_bf16 v[82:97], v[12:15], v[162:165], v[82:97]
	ds_read_b128 v[12:15], v3
	s_waitcnt vmcnt(2) lgkmcnt(2)
	v_mfma_f32_32x32x16_bf16 v[98:113], v[4:7], v[166:169], v[98:113]
	ds_read_b128 v[4:7], v3 offset:4096
	v_add_u32_e32 v3, v225, v230
	s_waitcnt lgkmcnt(2)
	v_mfma_f32_32x32x16_bf16 v[82:97], v[8:11], v[166:169], v[82:97]
	ds_read_b128 v[8:11], v3
	s_waitcnt vmcnt(1) lgkmcnt(2)
	v_mfma_f32_32x32x16_bf16 v[98:113], v[12:15], v[170:173], v[98:113]
	ds_read_b128 v[12:15], v3 offset:4096
	s_waitcnt lgkmcnt(2)
	v_mfma_f32_32x32x16_bf16 v[82:97], v[4:7], v[170:173], v[82:97]
	s_waitcnt vmcnt(0) lgkmcnt(1)
	v_mfma_f32_32x32x16_bf16 v[98:113], v[8:11], v[174:177], v[98:113]
	s_waitcnt lgkmcnt(0)
	v_mfma_f32_32x32x16_bf16 v[82:97], v[12:15], v[174:177], v[82:97]
	s_cbranch_scc1 .LBB0_391
	v_cmp_gt_i32_e64 s[68:69], 26, v218
	v_cmp_gt_i32_e64 s[70:71], 27, v218
	v_cmp_gt_i32_e64 s[66:67], 25, v218
	s_and_b64 s[68:69], s[70:71], s[68:69]
	v_cmp_gt_i32_e64 s[64:65], 24, v218
	s_and_b64 s[66:67], s[68:69], s[66:67]
	v_cmp_gt_i32_e64 s[62:63], 19, v218
	s_and_b64 s[64:65], s[66:67], s[64:65]
	v_cmp_gt_i32_e64 s[60:61], 18, v218
	s_and_b64 s[62:63], s[64:65], s[62:63]
	v_cmp_gt_i32_e64 s[58:59], 17, v218
	s_and_b64 s[60:61], s[62:63], s[60:61]
	v_cmp_gt_i32_e64 s[56:57], 16, v218
	s_and_b64 s[58:59], s[60:61], s[58:59]
	v_cmp_gt_i32_e64 s[54:55], 11, v218
	s_and_b64 s[56:57], s[58:59], s[56:57]
	v_cmp_gt_i32_e64 s[52:53], 10, v218
	s_and_b64 s[54:55], s[56:57], s[54:55]
	v_cmp_gt_i32_e64 s[50:51], 9, v218
	s_and_b64 s[52:53], s[54:55], s[52:53]
	v_cmp_gt_i32_e64 s[48:49], 8, v218
	s_and_b64 s[50:51], s[52:53], s[50:51]
	v_cmp_gt_i32_e64 s[46:47], 3, v218
	s_and_b64 s[48:49], s[50:51], s[48:49]
	v_cmp_gt_i32_e64 s[44:45], 2, v218
	s_and_b64 s[46:47], s[48:49], s[46:47]
	v_cmp_gt_i32_e64 s[42:43], 1, v218
	s_and_b64 s[44:45], s[46:47], s[44:45]
	v_cmp_gt_i32_e64 s[40:41], 0, v218
	s_and_b64 s[42:43], s[44:45], s[42:43]
	s_and_b64 s[40:41], s[42:43], s[40:41]
	v_cmp_gt_i32_e64 s[36:37], 58, v218
	v_cndmask_b32_e64 v98, v98, v210, s[40:41]
	v_cmp_gt_i32_e64 s[40:41], 59, v218
	v_cmp_gt_i32_e64 s[34:35], 57, v218
	s_and_b64 s[36:37], s[40:41], s[36:37]
	v_cmp_gt_i32_e64 s[30:31], 56, v218
	s_and_b64 s[34:35], s[36:37], s[34:35]
	v_cmp_gt_i32_e64 s[28:29], 51, v218
	s_and_b64 s[30:31], s[34:35], s[30:31]
	v_cmp_gt_i32_e64 s[26:27], 50, v218
	s_and_b64 s[28:29], s[30:31], s[28:29]
	v_cmp_gt_i32_e64 s[24:25], 49, v218
	s_and_b64 s[26:27], s[28:29], s[26:27]
	v_cmp_gt_i32_e64 s[22:23], 48, v218
	s_and_b64 s[24:25], s[26:27], s[24:25]
	v_cmp_gt_i32_e64 s[20:21], 43, v218
	s_and_b64 s[22:23], s[24:25], s[22:23]
	v_cmp_gt_i32_e64 s[18:19], 42, v218
	s_and_b64 s[20:21], s[22:23], s[20:21]
	v_cmp_gt_i32_e64 s[16:17], 41, v218
	s_and_b64 s[18:19], s[20:21], s[18:19]
	v_cmp_gt_i32_e64 s[14:15], 40, v218
	s_and_b64 s[16:17], s[18:19], s[16:17]
	v_cmp_gt_i32_e64 s[12:13], 35, v218
	s_and_b64 s[14:15], s[16:17], s[14:15]
	v_cmp_gt_i32_e64 s[10:11], 34, v218
	s_and_b64 s[12:13], s[14:15], s[12:13]
	v_cmp_gt_i32_e64 s[8:9], 33, v218
	s_and_b64 s[10:11], s[12:13], s[10:11]
	v_cmp_gt_i32_e32 vcc, 32, v218
	s_and_b64 s[8:9], s[10:11], s[8:9]
	s_and_b64 vcc, s[8:9], vcc
	v_cndmask_b32_e64 v113, v113, v210, s[70:71]
	v_cndmask_b32_e64 v112, v112, v210, s[68:69]
	v_cndmask_b32_e64 v111, v111, v210, s[66:67]
	v_cndmask_b32_e64 v110, v110, v210, s[64:65]
	v_cndmask_b32_e64 v109, v109, v210, s[62:63]
	v_cndmask_b32_e64 v108, v108, v210, s[60:61]
	v_cndmask_b32_e64 v107, v107, v210, s[58:59]
	v_cndmask_b32_e64 v106, v106, v210, s[56:57]
	v_cndmask_b32_e64 v105, v105, v210, s[54:55]
	v_cndmask_b32_e64 v104, v104, v210, s[52:53]
	v_cndmask_b32_e64 v103, v103, v210, s[50:51]
	v_cndmask_b32_e64 v102, v102, v210, s[48:49]
	v_cndmask_b32_e64 v101, v101, v210, s[46:47]
	v_cndmask_b32_e64 v100, v100, v210, s[44:45]
	v_cndmask_b32_e64 v99, v99, v210, s[42:43]
	v_cndmask_b32_e64 v97, v97, v210, s[40:41]
	v_cndmask_b32_e64 v96, v96, v210, s[36:37]
	v_cndmask_b32_e64 v95, v95, v210, s[34:35]
	v_cndmask_b32_e64 v94, v94, v210, s[30:31]
	v_cndmask_b32_e64 v93, v93, v210, s[28:29]
	v_cndmask_b32_e64 v92, v92, v210, s[26:27]
	v_cndmask_b32_e64 v91, v91, v210, s[24:25]
	v_cndmask_b32_e64 v90, v90, v210, s[22:23]
	v_cndmask_b32_e64 v89, v89, v210, s[20:21]
	v_cndmask_b32_e64 v88, v88, v210, s[18:19]
	v_cndmask_b32_e64 v87, v87, v210, s[16:17]
	v_cndmask_b32_e64 v86, v86, v210, s[14:15]
	v_cndmask_b32_e64 v85, v85, v210, s[12:13]
	v_cndmask_b32_e64 v84, v84, v210, s[10:11]
	v_cndmask_b32_e64 v83, v83, v210, s[8:9]
	v_cndmask_b32_e32 v82, v82, v210, vcc

.LBB0_397:
	ds_read_b128 v[4:7], v233 offset:49152
	ds_read_b128 v[8:11], v233 offset:57344
	ds_read_b128 v[12:15], v234 offset:49152
	v_add_u32_e32 v3, v231, v227
	s_add_i32 s0, s81, 64
	s_waitcnt vmcnt(11) lgkmcnt(2)
	v_mfma_f32_32x32x16_bf16 v[98:113], v[4:7], v[126:129], 0
	ds_read_b128 v[4:7], v234 offset:57344
	s_cmp_le_i32 s0, s80
	s_waitcnt lgkmcnt(2)
	v_mfma_f32_32x32x16_bf16 v[82:97], v[8:11], v[126:129], 0
	ds_read_b128 v[8:11], v235 offset:49152
	s_waitcnt vmcnt(10) lgkmcnt(2)
	v_mfma_f32_32x32x16_bf16 v[98:113], v[12:15], v[130:133], v[98:113]
	ds_read_b128 v[12:15], v235 offset:57344
	s_waitcnt lgkmcnt(2)
	v_mfma_f32_32x32x16_bf16 v[82:97], v[4:7], v[130:133], v[82:97]
	ds_read_b128 v[4:7], v236 offset:49152
	s_waitcnt vmcnt(9) lgkmcnt(2)
	v_mfma_f32_32x32x16_bf16 v[98:113], v[8:11], v[138:141], v[98:113]
	ds_read_b128 v[8:11], v236 offset:57344
	s_waitcnt lgkmcnt(2)
	v_mfma_f32_32x32x16_bf16 v[82:97], v[12:15], v[138:141], v[82:97]
	ds_read_b128 v[12:15], v237 offset:49152
	s_waitcnt vmcnt(8) lgkmcnt(2)
	v_mfma_f32_32x32x16_bf16 v[98:113], v[4:7], v[142:145], v[98:113]
	ds_read_b128 v[4:7], v237 offset:57344
	s_waitcnt lgkmcnt(2)
	v_mfma_f32_32x32x16_bf16 v[82:97], v[8:11], v[142:145], v[82:97]
	ds_read_b128 v[8:11], v238 offset:49152
	s_waitcnt vmcnt(7) lgkmcnt(2)
	v_mfma_f32_32x32x16_bf16 v[98:113], v[12:15], v[146:149], v[98:113]
	ds_read_b128 v[12:15], v238 offset:57344
	s_waitcnt lgkmcnt(2)
	v_mfma_f32_32x32x16_bf16 v[82:97], v[4:7], v[146:149], v[82:97]
	ds_read_b128 v[4:7], v239 offset:49152
	s_waitcnt vmcnt(6) lgkmcnt(2)
	v_mfma_f32_32x32x16_bf16 v[98:113], v[8:11], v[150:153], v[98:113]
	ds_read_b128 v[8:11], v239 offset:57344
	s_waitcnt lgkmcnt(2)
	v_mfma_f32_32x32x16_bf16 v[82:97], v[12:15], v[150:153], v[82:97]
	ds_read_b128 v[12:15], v240 offset:49152
	s_waitcnt vmcnt(5) lgkmcnt(2)
	v_mfma_f32_32x32x16_bf16 v[98:113], v[4:7], v[154:157], v[98:113]
	ds_read_b128 v[4:7], v240 offset:57344
	s_waitcnt lgkmcnt(2)
	v_mfma_f32_32x32x16_bf16 v[82:97], v[8:11], v[154:157], v[82:97]
	ds_read_b128 v[8:11], v3
	s_waitcnt vmcnt(4) lgkmcnt(2)
	v_mfma_f32_32x32x16_bf16 v[98:113], v[12:15], v[158:161], v[98:113]
	ds_read_b128 v[12:15], v3 offset:4096
	v_add_u32_e32 v3, v231, v228
	s_waitcnt lgkmcnt(2)
	v_mfma_f32_32x32x16_bf16 v[82:97], v[4:7], v[158:161], v[82:97]
	ds_read_b128 v[4:7], v3
	s_waitcnt vmcnt(3) lgkmcnt(2)
	v_mfma_f32_32x32x16_bf16 v[98:113], v[8:11], v[162:165], v[98:113]
	ds_read_b128 v[8:11], v3 offset:4096
	v_add_u32_e32 v3, v231, v229
	s_waitcnt lgkmcnt(2)
	v_mfma_f32_32x32x16_bf16 v[82:97], v[12:15], v[162:165], v[82:97]
	ds_read_b128 v[12:15], v3
	s_waitcnt vmcnt(2) lgkmcnt(2)
	v_mfma_f32_32x32x16_bf16 v[98:113], v[4:7], v[166:169], v[98:113]
	ds_read_b128 v[4:7], v3 offset:4096
	v_add_u32_e32 v3, v231, v230
	s_waitcnt lgkmcnt(2)
	v_mfma_f32_32x32x16_bf16 v[82:97], v[8:11], v[166:169], v[82:97]
	ds_read_b128 v[8:11], v3
	s_waitcnt vmcnt(1) lgkmcnt(2)
	v_mfma_f32_32x32x16_bf16 v[98:113], v[12:15], v[170:173], v[98:113]
	ds_read_b128 v[12:15], v3 offset:4096
	s_waitcnt lgkmcnt(2)
	v_mfma_f32_32x32x16_bf16 v[82:97], v[4:7], v[170:173], v[82:97]
	s_waitcnt vmcnt(0) lgkmcnt(1)
	v_mfma_f32_32x32x16_bf16 v[98:113], v[8:11], v[174:177], v[98:113]
	s_waitcnt lgkmcnt(0)
	v_mfma_f32_32x32x16_bf16 v[82:97], v[12:15], v[174:177], v[82:97]
	s_cbranch_scc1 .LBB0_399
	v_subrev_u32_e32 v3, 64, v218
	v_cmp_gt_i32_e64 s[68:69], 26, v3
	v_cmp_gt_i32_e64 s[70:71], 27, v3
	v_cmp_gt_i32_e64 s[66:67], 25, v3
	s_and_b64 s[68:69], s[70:71], s[68:69]
	v_cmp_gt_i32_e64 s[64:65], 24, v3
	s_and_b64 s[66:67], s[68:69], s[66:67]
	v_cmp_gt_i32_e64 s[62:63], 19, v3
	s_and_b64 s[64:65], s[66:67], s[64:65]
	v_cmp_gt_i32_e64 s[60:61], 18, v3
	s_and_b64 s[62:63], s[64:65], s[62:63]
	v_cmp_gt_i32_e64 s[58:59], 17, v3
	s_and_b64 s[60:61], s[62:63], s[60:61]
	v_cmp_gt_i32_e64 s[56:57], 16, v3
	s_and_b64 s[58:59], s[60:61], s[58:59]
	v_cmp_gt_i32_e64 s[54:55], 11, v3
	s_and_b64 s[56:57], s[58:59], s[56:57]
	v_cmp_gt_i32_e64 s[52:53], 10, v3
	s_and_b64 s[54:55], s[56:57], s[54:55]
	v_cmp_gt_i32_e64 s[50:51], 9, v3
	s_and_b64 s[52:53], s[54:55], s[52:53]
	v_cmp_gt_i32_e64 s[48:49], 8, v3
	s_and_b64 s[50:51], s[52:53], s[50:51]
	v_cmp_gt_i32_e64 s[46:47], 3, v3
	s_and_b64 s[48:49], s[50:51], s[48:49]
	v_cmp_gt_i32_e64 s[44:45], 2, v3
	s_and_b64 s[46:47], s[48:49], s[46:47]
	v_cmp_gt_i32_e64 s[42:43], 1, v3
	s_and_b64 s[44:45], s[46:47], s[44:45]
	v_cmp_gt_i32_e64 s[40:41], 0, v3
	s_and_b64 s[42:43], s[44:45], s[42:43]
	s_and_b64 s[40:41], s[42:43], s[40:41]
	v_cmp_gt_i32_e64 s[36:37], 58, v3
	v_cndmask_b32_e64 v98, v98, v210, s[40:41]
	v_cmp_gt_i32_e64 s[40:41], 59, v3
	v_cmp_gt_i32_e64 s[34:35], 57, v3
	s_and_b64 s[36:37], s[40:41], s[36:37]
	v_cmp_gt_i32_e64 s[30:31], 56, v3
	s_and_b64 s[34:35], s[36:37], s[34:35]
	v_cmp_gt_i32_e64 s[28:29], 51, v3
	s_and_b64 s[30:31], s[34:35], s[30:31]
	v_cmp_gt_i32_e64 s[26:27], 50, v3
	s_and_b64 s[28:29], s[30:31], s[28:29]
	v_cmp_gt_i32_e64 s[24:25], 49, v3
	s_and_b64 s[26:27], s[28:29], s[26:27]
	v_cmp_gt_i32_e64 s[22:23], 48, v3
	s_and_b64 s[24:25], s[26:27], s[24:25]
	v_cmp_gt_i32_e64 s[20:21], 43, v3
	s_and_b64 s[22:23], s[24:25], s[22:23]
	v_cmp_gt_i32_e64 s[18:19], 42, v3
	s_and_b64 s[20:21], s[22:23], s[20:21]
	v_cmp_gt_i32_e64 s[16:17], 41, v3
	s_and_b64 s[18:19], s[20:21], s[18:19]
	v_cmp_gt_i32_e64 s[14:15], 40, v3
	s_and_b64 s[16:17], s[18:19], s[16:17]
	v_cmp_gt_i32_e64 s[12:13], 35, v3
	s_and_b64 s[14:15], s[16:17], s[14:15]
	v_cmp_gt_i32_e64 s[10:11], 34, v3
	s_and_b64 s[12:13], s[14:15], s[12:13]
	v_cmp_gt_i32_e64 s[8:9], 33, v3
	s_and_b64 s[10:11], s[12:13], s[10:11]
	v_cmp_gt_i32_e32 vcc, 32, v3
	s_and_b64 s[8:9], s[10:11], s[8:9]
	s_and_b64 vcc, s[8:9], vcc
	v_cndmask_b32_e64 v113, v113, v210, s[70:71]
	v_cndmask_b32_e64 v112, v112, v210, s[68:69]
	v_cndmask_b32_e64 v111, v111, v210, s[66:67]
	v_cndmask_b32_e64 v110, v110, v210, s[64:65]
	v_cndmask_b32_e64 v109, v109, v210, s[62:63]
	v_cndmask_b32_e64 v108, v108, v210, s[60:61]
	v_cndmask_b32_e64 v107, v107, v210, s[58:59]
	v_cndmask_b32_e64 v106, v106, v210, s[56:57]
	v_cndmask_b32_e64 v105, v105, v210, s[54:55]
	v_cndmask_b32_e64 v104, v104, v210, s[52:53]
	v_cndmask_b32_e64 v103, v103, v210, s[50:51]
	v_cndmask_b32_e64 v102, v102, v210, s[48:49]
	v_cndmask_b32_e64 v101, v101, v210, s[46:47]
	v_cndmask_b32_e64 v100, v100, v210, s[44:45]
	v_cndmask_b32_e64 v99, v99, v210, s[42:43]
	v_cndmask_b32_e64 v97, v97, v210, s[40:41]
	v_cndmask_b32_e64 v96, v96, v210, s[36:37]
	v_cndmask_b32_e64 v95, v95, v210, s[34:35]
	v_cndmask_b32_e64 v94, v94, v210, s[30:31]
	v_cndmask_b32_e64 v93, v93, v210, s[28:29]
	v_cndmask_b32_e64 v92, v92, v210, s[26:27]
	v_cndmask_b32_e64 v91, v91, v210, s[24:25]
	v_cndmask_b32_e64 v90, v90, v210, s[22:23]
	v_cndmask_b32_e64 v89, v89, v210, s[20:21]
	v_cndmask_b32_e64 v88, v88, v210, s[18:19]
	v_cndmask_b32_e64 v87, v87, v210, s[16:17]
	v_cndmask_b32_e64 v86, v86, v210, s[14:15]
	v_cndmask_b32_e64 v85, v85, v210, s[12:13]
	v_cndmask_b32_e64 v84, v84, v210, s[10:11]
	v_cndmask_b32_e64 v83, v83, v210, s[8:9]
	v_cndmask_b32_e32 v82, v82, v210, vcc
